# natten step: the four gate loads are issued at the start of the QK block (after the q prefetch) instead of just before P.V; they land in the VGPR pairs of StaticOrder's 64-bit constants, restored afte
# speedup vs baseline: 1.0076x; 1.0076x over previous
.LBB0_482:
	v_lshl_add_u64 v[210:211], v[126:127], 0, s[34:35]
	global_load_dwordx2 v[190:191], v[210:211], off offset:-64
	global_load_dwordx2 v[192:193], v[210:211], off offset:-32
	global_load_dwordx2 v[198:199], v[210:211], off
	global_load_dwordx2 v[200:201], v[210:211], off offset:32
	s_max_i32 s69, s86, 4
	s_add_i32 s69, s69, -4
	s_min_u32 s69, s69, 56
	s_add_i32 s69, s69, s81
	s_add_i32 s70, s19, s80
	s_max_i32 s70, s70, 4
	s_mul_i32 s69, s69, 31
	s_add_i32 s70, s70, -4
	v_add_lshl_u32 v32, v173, s69, 2
	s_min_u32 s70, s70, 56
	v_add_u32_e32 v33, 0x2143c, v32
	s_mul_i32 s71, s70, 47
	v_cndmask_b32_e64 v44, v214, v33, s[46:47]
	v_add_u32_e32 v33, 0x21440, v32
	s_lshr_b32 s71, s71, 9
	v_cndmask_b32_e64 v45, v214, v33, s[48:49]
	v_add_u32_e32 v33, 0x21444, v32
	s_mul_i32 s71, s71, 11
	v_cndmask_b32_e64 v46, v214, v33, s[50:51]
	v_add_u32_e32 v33, 0x21448, v32
	s_sub_i32 s70, s70, s71
	v_cndmask_b32_e64 v47, v214, v33, s[52:53]
	v_add_u32_e32 v33, 0x2147c, v32
	v_cndmask_b32_e64 v52, v214, v33, s[54:55]
	v_add_u32_e32 v33, 0x21480, v32
	s_and_b32 s69, s70, 0xff
	v_cndmask_b32_e64 v54, v214, v33, s[56:57]
	v_add_u32_e32 v33, 0x21484, v32
	v_add_u32_e32 v32, 0x21488, v32
	s_mul_i32 s70, s69, 0x1800
	v_cndmask_b32_e64 v58, v214, v32, s[60:61]
	v_add_u32_e32 v32, s70, v174
	v_add_u32_e32 v36, v32, v171
	v_add_u32_e32 v48, v32, v172
	v_add_u32_e32 v90, 0, v45
	v_cndmask_b32_e64 v55, v214, v33, s[58:59]
	ds_read_b128 v[32:35], v36
	ds_read_b128 v[36:39], v36 offset:2048
	ds_read_b128 v[40:43], v48
	ds_read_b128 v[48:51], v48 offset:2048
	v_add_u32_e32 v89, 0, v52
	ds_read2_b32 v[52:53], v90 offset1:31
	v_add_u32_e32 v94, 0, v47
	v_add_u32_e32 v91, 0, v54
	v_add_u32_e32 v93, 0, v55
	ds_read2_b32 v[54:55], v94 offset1:31
	s_cmp_gt_u32 s69, 9
	s_cselect_b32 s70, -10, 1
	s_add_i32 s70, s70, s69
	s_mul_i32 s71, s70, 0x1800
	s_waitcnt lgkmcnt(1)
	v_mov_b32_e32 v45, v52
	v_add_u32_e32 v52, s71, v174
	v_add_u32_e32 v88, 0, v44
	v_add_u32_e32 v92, 0, v46
	v_add_u32_e32 v95, 0, v58
	s_waitcnt lgkmcnt(0)
	v_mov_b32_e32 v47, v54
	v_add_u32_e32 v54, v52, v171
	ds_read2_b32 v[96:97], v88 offset1:31
	ds_read2_b32 v[98:99], v89 offset1:31
	ds_read2_b32 v[56:57], v91 offset1:31
	ds_read2_b32 v[132:133], v92 offset1:31
	ds_read2_b32 v[134:135], v93 offset1:31
	ds_read2_b32 v[58:59], v95 offset1:31
	v_add_u32_e32 v52, v52, v172
	ds_read_b128 v[64:67], v54
	ds_read_b128 v[68:71], v54 offset:2048
	ds_read_b128 v[72:75], v52
	ds_read_b128 v[76:79], v52 offset:2048
	s_waitcnt lgkmcnt(9)
	v_mov_b32_e32 v44, v96
	s_waitcnt lgkmcnt(6)
	v_mov_b32_e32 v46, v132
	v_mov_b32_e32 v60, v98
	v_mov_b32_e32 v61, v56
	s_waitcnt lgkmcnt(5)
	v_mov_b32_e32 v62, v134
	s_waitcnt lgkmcnt(4)
	v_mov_b32_e32 v63, v58
	v_mov_b32_e32 v52, v97
	v_mov_b32_e32 v54, v133
	v_mov_b32_e32 v56, v99
	v_mov_b32_e32 v58, v135
	v_mfma_f32_16x16x32_bf16 v[32:35], v[32:35], v[80:83], v[44:47]
	v_mfma_f32_16x16x32_bf16 v[36:39], v[36:39], v[80:83], v[60:63]
	v_mfma_f32_16x16x32_bf16 v[44:47], v[40:43], v[84:87], v[32:35]
	v_mfma_f32_16x16x32_bf16 v[40:43], v[48:51], v[84:87], v[36:39]
	s_cmp_gt_u32 s69, 8
	s_cselect_b32 s82, -9, 2
	s_add_i32 s82, s82, s69
	s_mul_i32 s71, s82, 0x1800
	s_nop 0
	v_add_u32_e32 v32, s71, v174
	v_add_u32_e32 v33, v32, v171
	v_add_u32_e32 v32, v32, v172
	ds_read_b128 v[48:51], v33
	ds_read_b128 v[60:63], v33 offset:2048
	ds_read_b128 v[96:99], v32
	ds_read_b128 v[132:135], v32 offset:2048
	ds_read_b32 v180, v88 offset:248
	ds_read_b32 v184, v89 offset:248
	ds_read_b32 v181, v90 offset:248
	ds_read_b32 v185, v91 offset:248
	ds_read_b32 v182, v92 offset:248
	ds_read_b32 v186, v93 offset:248
	ds_read_b32 v183, v94 offset:248
	ds_read_b32 v187, v95 offset:248
	s_waitcnt lgkmcnt(14)
	v_mfma_f32_16x16x32_bf16 v[32:35], v[64:67], v[80:83], v[52:55]
	s_mov_b32 s71, 0xf149f2ca
	v_mfma_f32_16x16x32_bf16 v[52:55], v[68:71], v[80:83], v[56:59]
	s_waitcnt lgkmcnt(13)
	v_mfma_f32_16x16x32_bf16 v[36:39], v[72:75], v[84:87], v[32:35]
	s_waitcnt lgkmcnt(12)
	v_mfma_f32_16x16x32_bf16 v[32:35], v[76:79], v[84:87], v[52:55]
	s_nop 3
	v_max_f32_e32 v52, v45, v45
	v_max_f32_e32 v53, v44, v44
	v_max_f32_e32 v52, v53, v52
	v_max_f32_e32 v53, v47, v47
	v_max_f32_e32 v54, v46, v46
	v_max_f32_e32 v53, v54, v53
	v_max3_f32 v52, v52, s71, v53
	v_max_f32_e32 v53, v41, v41
	v_max_f32_e32 v54, v40, v40
	v_max_f32_e32 v53, v54, v53
	v_max_f32_e32 v54, v43, v43
	v_max_f32_e32 v55, v42, v42
	v_max_f32_e32 v54, v55, v54
	v_max3_f32 v179, v52, v53, v54
	s_cmp_gt_u32 s69, 7
	s_cselect_b32 s83, -8, 3
	s_add_i32 s83, s83, s69
	s_mul_i32 s71, s83, 0x1800
	v_add_u32_e32 v52, s71, v174
	v_add_u32_e32 v53, v52, v171
	v_add_u32_e32 v52, v52, v172
	ds_read_b128 v[56:59], v53
	ds_read_b128 v[64:67], v53 offset:2048
	ds_read_b128 v[68:71], v52
	ds_read_b128 v[72:75], v52 offset:2048
	ds_read_b32 v76, v88 offset:372
	ds_read_b32 v202, v89 offset:372
	ds_read_b32 v77, v90 offset:372
	ds_read_b32 v203, v91 offset:372
	ds_read_b32 v78, v92 offset:372
	ds_read_b32 v204, v93 offset:372
	ds_read_b32 v79, v94 offset:372
	ds_read_b32 v205, v95 offset:372
	s_waitcnt lgkmcnt(13)
	v_mfma_f32_16x16x32_bf16 v[48:51], v[48:51], v[80:83], v[180:183]
	s_waitcnt lgkmcnt(12)
	v_mfma_f32_16x16x32_bf16 v[60:63], v[60:63], v[80:83], v[184:187]
	v_mfma_f32_16x16x32_bf16 v[52:55], v[96:99], v[84:87], v[48:51]
	v_mfma_f32_16x16x32_bf16 v[48:51], v[132:135], v[84:87], v[60:63]
	s_nop 5
	v_max_f32_e32 v60, v37, v37
	v_max_f32_e32 v61, v36, v36
	v_max_f32_e32 v60, v61, v60
	v_max_f32_e32 v61, v39, v39
	v_max_f32_e32 v62, v38, v38
	v_max_f32_e32 v61, v62, v61
	v_max3_f32 v60, v179, v60, v61
	v_max_f32_e32 v61, v33, v33
	v_max_f32_e32 v62, v32, v32
	v_max_f32_e32 v61, v62, v61
	v_max_f32_e32 v62, v35, v35
	v_max_f32_e32 v63, v34, v34
	v_max_f32_e32 v62, v63, v62
	v_max3_f32 v179, v60, v61, v62
	s_cmp_gt_u32 s69, 6
	s_cselect_b32 s84, -7, 4
	s_add_i32 s84, s84, s69
	s_mul_i32 s71, s84, 0x1800
	v_add_u32_e32 v60, s71, v174
	v_add_u32_e32 v61, v60, v171
	v_add_u32_e32 v60, v60, v172
	ds_read_b128 v[96:99], v61
	ds_read_b128 v[132:135], v61 offset:2048
	ds_read_b128 v[180:183], v60
	ds_read_b128 v[184:187], v60 offset:2048
	ds_read_b32 v216, v88 offset:496
	ds_read_b32 v220, v89 offset:496
	ds_read_b32 v217, v90 offset:496
	ds_read_b32 v221, v91 offset:496
	ds_read_b32 v218, v92 offset:496
	ds_read_b32 v222, v93 offset:496
	ds_read_b32 v219, v94 offset:496
	ds_read_b32 v223, v95 offset:496
	s_waitcnt lgkmcnt(13)
	v_mfma_f32_16x16x32_bf16 v[56:59], v[56:59], v[80:83], v[76:79]
	s_waitcnt lgkmcnt(12)
	v_mfma_f32_16x16x32_bf16 v[64:67], v[64:67], v[80:83], v[202:205]
	v_mfma_f32_16x16x32_bf16 v[60:63], v[68:71], v[84:87], v[56:59]
	v_mfma_f32_16x16x32_bf16 v[56:59], v[72:75], v[84:87], v[64:67]
	s_nop 5
	v_max_f32_e32 v64, v53, v53
	v_max_f32_e32 v65, v52, v52
	v_max_f32_e32 v64, v65, v64
	v_max_f32_e32 v65, v55, v55
	v_max_f32_e32 v66, v54, v54
	v_max_f32_e32 v65, v66, v65
	v_max3_f32 v64, v179, v64, v65
	v_max_f32_e32 v65, v49, v49
	v_max_f32_e32 v66, v48, v48
	v_max_f32_e32 v65, v66, v65
	v_max_f32_e32 v66, v51, v51
	v_max_f32_e32 v67, v50, v50
	v_max_f32_e32 v66, v67, v66
	v_max3_f32 v179, v64, v65, v66
	s_cmp_gt_u32 s69, 5
	s_cselect_b32 s85, -6, 5
	s_add_i32 s85, s85, s69
	s_mul_i32 s71, s85, 0x1800
	v_add_u32_e32 v64, s71, v174
	v_add_u32_e32 v65, v64, v171
	v_add_u32_e32 v64, v64, v172
	ds_read_b128 v[72:75], v65
	ds_read_b128 v[76:79], v65 offset:2048
	ds_read_b128 v[202:205], v64
	ds_read_b128 v[224:227], v64 offset:2048
	ds_read_b32 v228, v88 offset:620
	ds_read_b32 v232, v89 offset:620
	ds_read_b32 v229, v90 offset:620
	ds_read_b32 v233, v91 offset:620
	ds_read_b32 v230, v92 offset:620
	ds_read_b32 v234, v93 offset:620
	ds_read_b32 v231, v94 offset:620
	ds_read_b32 v235, v95 offset:620
	s_waitcnt lgkmcnt(13)
	v_mfma_f32_16x16x32_bf16 v[64:67], v[96:99], v[80:83], v[216:219]
	s_waitcnt lgkmcnt(12)
	v_mfma_f32_16x16x32_bf16 v[96:99], v[132:135], v[80:83], v[220:223]
	v_mfma_f32_16x16x32_bf16 v[68:71], v[180:183], v[84:87], v[64:67]
	v_mfma_f32_16x16x32_bf16 v[64:67], v[184:187], v[84:87], v[96:99]
	s_nop 5
	v_max_f32_e32 v96, v61, v61
	v_max_f32_e32 v97, v60, v60
	v_max_f32_e32 v96, v97, v96
	v_max_f32_e32 v97, v63, v63
	v_max_f32_e32 v98, v62, v62
	v_max_f32_e32 v97, v98, v97
	v_max3_f32 v96, v179, v96, v97
	v_max_f32_e32 v97, v57, v57
	v_max_f32_e32 v98, v56, v56
	v_max_f32_e32 v97, v98, v97
	v_max_f32_e32 v98, v59, v59
	v_max_f32_e32 v99, v58, v58
	v_max_f32_e32 v98, v99, v98
	v_max3_f32 v179, v96, v97, v98
	s_cmp_gt_u32 s69, 4
	s_cselect_b32 s89, -5, 6
	s_add_i32 s89, s89, s69
	s_mul_i32 s71, s89, 0x1800
	v_add_u32_e32 v96, s71, v174
	v_add_u32_e32 v132, v96, v171
	v_add_u32_e32 v184, v96, v172
	ds_read_b128 v[96:99], v132
	ds_read_b128 v[132:135], v132 offset:2048
	ds_read_b128 v[180:183], v184
	ds_read_b128 v[184:187], v184 offset:2048
	ds_read_b32 v216, v88 offset:744
	ds_read_b32 v220, v89 offset:744
	ds_read_b32 v217, v90 offset:744
	ds_read_b32 v221, v91 offset:744
	ds_read_b32 v218, v92 offset:744
	ds_read_b32 v222, v93 offset:744
	ds_read_b32 v219, v94 offset:744
	ds_read_b32 v223, v95 offset:744
	s_waitcnt lgkmcnt(13)
	v_mfma_f32_16x16x32_bf16 v[72:75], v[72:75], v[80:83], v[228:231]
	v_max_f32_e32 v194, v69, v69
	v_max_f32_e32 v195, v68, v68
	v_max_f32_e32 v194, v195, v194
	s_waitcnt lgkmcnt(12)
	v_mfma_f32_16x16x32_bf16 v[228:231], v[76:79], v[80:83], v[232:235]
	v_max_f32_e32 v195, v71, v71
	v_max_f32_e32 v196, v70, v70
	v_max_f32_e32 v195, v196, v195
	v_mfma_f32_16x16x32_bf16 v[76:79], v[202:205], v[84:87], v[72:75]
	v_max3_f32 v179, v179, v194, v195
	v_max_f32_e32 v194, v65, v65
	v_max_f32_e32 v195, v64, v64
	v_mfma_f32_16x16x32_bf16 v[72:75], v[224:227], v[84:87], v[228:231]
	v_max_f32_e32 v194, v195, v194
	v_max_f32_e32 v195, v67, v67
	v_max_f32_e32 v196, v66, v66
	v_max_f32_e32 v195, v196, v195
	v_max3_f32 v179, v179, v194, v195
	s_cmp_gt_u32 s69, 3
	s_cselect_b32 s94, -4, 7
	s_add_i32 s94, s94, s69
	s_mul_i32 s71, s94, 0x1800
	v_add_u32_e32 v194, s71, v174
	v_add_u32_e32 v195, v194, v171
	v_add_u32_e32 v194, v194, v172
	ds_read_b128 v[202:205], v195
	ds_read_b128 v[224:227], v195 offset:2048
	ds_read_b128 v[228:231], v194
	ds_read_b128 v[232:235], v194 offset:2048
	ds_read_b32 v236, v88 offset:868
	ds_read_b32 v240, v89 offset:868
	ds_read_b32 v237, v90 offset:868
	ds_read_b32 v241, v91 offset:868
	ds_read_b32 v238, v92 offset:868
	ds_read_b32 v242, v93 offset:868
	ds_read_b32 v239, v94 offset:868
	ds_read_b32 v243, v95 offset:868
	s_waitcnt lgkmcnt(13)
	v_mfma_f32_16x16x32_bf16 v[88:91], v[96:99], v[80:83], v[216:219]
	s_waitcnt lgkmcnt(12)
	v_mfma_f32_16x16x32_bf16 v[96:99], v[132:135], v[80:83], v[220:223]
	v_mfma_f32_16x16x32_bf16 v[92:95], v[180:183], v[84:87], v[88:91]
	v_mfma_f32_16x16x32_bf16 v[88:91], v[184:187], v[84:87], v[96:99]
	s_nop 5
	v_max_f32_e32 v96, v77, v77
	v_max_f32_e32 v97, v76, v76
	v_max_f32_e32 v96, v97, v96
	v_max_f32_e32 v97, v79, v79
	v_max_f32_e32 v98, v78, v78
	v_max_f32_e32 v97, v98, v97
	v_max3_f32 v96, v179, v96, v97
	v_max_f32_e32 v97, v73, v73
	v_max_f32_e32 v98, v72, v72
	v_max_f32_e32 v97, v98, v97
	v_max_f32_e32 v98, v75, v75
	v_max_f32_e32 v99, v74, v74
	v_max_f32_e32 v98, v99, v98
	v_max3_f32 v132, v96, v97, v98
	s_waitcnt lgkmcnt(1)
	v_mfma_f32_16x16x32_bf16 v[96:99], v[202:205], v[80:83], v[236:239]
	s_waitcnt lgkmcnt(0)
	v_mfma_f32_16x16x32_bf16 v[80:83], v[224:227], v[80:83], v[240:243]
	v_mfma_f32_16x16x32_bf16 v[96:99], v[228:231], v[84:87], v[96:99]
	v_mfma_f32_16x16x32_bf16 v[80:83], v[232:235], v[84:87], v[80:83]
	v_max_f32_e32 v84, v93, v93
	v_max_f32_e32 v85, v92, v92
	v_max_f32_e32 v84, v85, v84
	v_max_f32_e32 v85, v95, v95
	v_max_f32_e32 v86, v94, v94
	v_max_f32_e32 v85, v86, v85
	v_max3_f32 v84, v132, v84, v85
	v_max_f32_e32 v85, v89, v89
	v_max_f32_e32 v86, v88, v88
	v_max_f32_e32 v85, v86, v85
	v_max_f32_e32 v86, v91, v91
	v_max_f32_e32 v87, v90, v90
	v_max_f32_e32 v86, v87, v86
	v_max3_f32 v84, v84, v85, v86
	v_max_f32_e32 v85, v97, v97
	v_max_f32_e32 v86, v96, v96
	v_max_f32_e32 v85, v86, v85
	v_max_f32_e32 v86, v99, v99
	v_max_f32_e32 v87, v98, v98
	v_max_f32_e32 v86, v87, v86
	v_max3_f32 v84, v84, v85, v86
	v_max_f32_e32 v85, v81, v81
	v_max_f32_e32 v86, v80, v80
	v_max_f32_e32 v85, v86, v85
	v_max_f32_e32 v86, v83, v83
	v_max_f32_e32 v87, v82, v82
	v_max_f32_e32 v86, v87, v86
	v_max3_f32 v84, v84, v85, v86
	ds_bpermute_b32 v85, v175, v84
	s_mov_b32 s71, 0x42800000
	s_waitcnt lgkmcnt(0)
	v_max_f32_e32 v85, v85, v85
	v_max_f32_e32 v84, v84, v85
	ds_bpermute_b32 v85, v176, v84
	s_waitcnt lgkmcnt(0)
	v_max_f32_e32 v85, v85, v85
	v_max_f32_e32 v84, v84, v85
	v_cmp_gt_f32_e64 vcc, |v84|, s71
	s_cbranch_vccnz .LBB0_497
.LBB0_483:
	s_mulk_i32 s69, 0x60
	v_add_u32_e32 v179, s69, v177
	s_mulk_i32 s70, 0x60
	v_add_u32_e32 v194, s69, v178
	ds_read_b64 v[180:181], v179
	ds_read_b64 v[184:185], v179 offset:17152
	ds_read_b64 v[202:203], v179 offset:34304
	ds_read_b64 v[216:217], v179 offset:51456
	ds_read_b64 v[182:183], v194
	ds_read_b64 v[186:187], v194 offset:17152
	ds_read_b64 v[204:205], v194 offset:34304
	ds_read_b64 v[218:219], v194 offset:51456
	v_add_u32_e32 v179, s70, v177
	v_add_u32_e32 v194, s70, v178
	ds_read_b64 v[220:221], v179
	ds_read_b64 v[224:225], v179 offset:17152
	ds_read_b64 v[228:229], v179 offset:34304
	ds_read_b64 v[232:233], v179 offset:51456
	ds_read_b64 v[222:223], v194
	ds_read_b64 v[226:227], v194 offset:17152
	ds_read_b64 v[230:231], v194 offset:34304
	ds_read_b64 v[234:235], v194 offset:51456
	v_exp_f32_e32 v44, v44
	v_exp_f32_e32 v40, v40
	v_exp_f32_e32 v45, v45
	v_exp_f32_e32 v41, v41
	v_exp_f32_e32 v46, v46
	v_exp_f32_e32 v47, v47
	v_exp_f32_e32 v42, v42
	v_exp_f32_e32 v43, v43
	v_cvt_pk_bf16_f32 v44, v44, v45
	v_cvt_pk_bf16_f32 v45, v46, v47
	v_cvt_pk_bf16_f32 v46, v40, v41
	v_cvt_pk_bf16_f32 v47, v42, v43
	s_waitcnt lgkmcnt(11)
	s_nop 0
	v_mfma_f32_16x16x32_bf16 v[180:183], v[180:183], v[44:47], 0
	s_waitcnt lgkmcnt(10)
	v_mfma_f32_16x16x32_bf16 v[184:187], v[184:187], v[44:47], 0
	s_waitcnt lgkmcnt(9)
	v_mfma_f32_16x16x32_bf16 v[202:205], v[202:205], v[44:47], 0
	s_waitcnt lgkmcnt(8)
	v_mfma_f32_16x16x32_bf16 v[216:219], v[216:219], v[44:47], 0
	s_mulk_i32 s82, 0x60
	v_add_u32_e32 v179, s82, v177
	v_add_u32_e32 v196, s82, v178
	ds_read_b64 v[236:237], v179
	ds_read_b64 v[240:241], v179 offset:17152
	ds_read_b64 v[244:245], v179 offset:34304
	ds_read_b64 v[194:195], v179 offset:51456
	ds_read_b64 v[238:239], v196
	ds_read_b64 v[242:243], v196 offset:17152
	ds_read_b64 v[246:247], v196 offset:34304
	ds_read_b64 v[196:197], v196 offset:51456
	s_mov_b32 s26, s24
	s_mov_b32 s27, s24
	s_mov_b32 s25, s24
	v_mov_b64_e32 v[42:43], s[26:27]
	v_mov_b64_e32 v[40:41], s[24:25]
	v_exp_f32_e32 v36, v36
	v_exp_f32_e32 v179, v32
	v_exp_f32_e32 v32, v37
	v_exp_f32_e32 v37, v33
	v_exp_f32_e32 v33, v38
	v_exp_f32_e32 v38, v39
	v_exp_f32_e32 v39, v34
	v_exp_f32_e32 v35, v35
	v_mfma_f32_16x16x32_bf16 v[44:47], v[40:43], v[44:47], 0
	v_cvt_pk_bf16_f32 v32, v36, v32
	v_cvt_pk_bf16_f32 v33, v33, v38
	v_cvt_pk_bf16_f32 v34, v179, v37
	v_cvt_pk_bf16_f32 v35, v39, v35
	s_waitcnt lgkmcnt(11)
	s_nop 0
	v_mfma_f32_16x16x32_bf16 v[36:39], v[220:223], v[32:35], v[180:183]
	s_waitcnt lgkmcnt(10)
	v_mfma_f32_16x16x32_bf16 v[180:183], v[224:227], v[32:35], v[184:187]
	s_waitcnt lgkmcnt(9)
	v_mfma_f32_16x16x32_bf16 v[184:187], v[228:231], v[32:35], v[202:205]
	s_waitcnt lgkmcnt(8)
	v_mfma_f32_16x16x32_bf16 v[202:205], v[232:235], v[32:35], v[216:219]
	s_mulk_i32 s83, 0x60
	v_add_u32_e32 v179, s83, v177
	v_mfma_f32_16x16x32_bf16 v[32:35], v[40:43], v[32:35], v[44:47]
	v_add_u32_e32 v215, s83, v178
	s_nop 1
	ds_read_b64 v[44:45], v179
	ds_read_b64 v[216:217], v179 offset:17152
	ds_read_b64 v[220:221], v179 offset:34304
	ds_read_b64 v[224:225], v179 offset:51456
	ds_read_b64 v[46:47], v215
	ds_read_b64 v[218:219], v215 offset:17152
	ds_read_b64 v[222:223], v215 offset:34304
	ds_read_b64 v[226:227], v215 offset:51456
	v_exp_f32_e32 v52, v52
	v_exp_f32_e32 v179, v48
	v_exp_f32_e32 v48, v53
	v_exp_f32_e32 v53, v49
	v_exp_f32_e32 v49, v54
	v_exp_f32_e32 v54, v55
	v_exp_f32_e32 v55, v50
	v_exp_f32_e32 v51, v51
	v_cvt_pk_bf16_f32 v48, v52, v48
	v_cvt_pk_bf16_f32 v49, v49, v54
	v_cvt_pk_bf16_f32 v50, v179, v53
	v_cvt_pk_bf16_f32 v51, v55, v51
	s_waitcnt lgkmcnt(11)
	s_nop 0
	v_mfma_f32_16x16x32_bf16 v[36:39], v[236:239], v[48:51], v[36:39]
	s_waitcnt lgkmcnt(10)
	v_mfma_f32_16x16x32_bf16 v[52:55], v[240:243], v[48:51], v[180:183]
	s_waitcnt lgkmcnt(9)
	v_mfma_f32_16x16x32_bf16 v[180:183], v[244:247], v[48:51], v[184:187]
	s_waitcnt lgkmcnt(8)
	v_mfma_f32_16x16x32_bf16 v[184:187], v[194:197], v[48:51], v[202:205]
	s_mulk_i32 s84, 0x60
	v_add_u32_e32 v179, s84, v177
	v_mfma_f32_16x16x32_bf16 v[32:35], v[40:43], v[48:51], v[32:35]
	v_add_u32_e32 v215, s84, v178
	ds_read_b64 v[48:49], v179
	ds_read_b64 v[194:195], v179 offset:17152
	ds_read_b64 v[202:203], v179 offset:34304
	ds_read_b64 v[228:229], v179 offset:51456
	ds_read_b64 v[50:51], v215
	ds_read_b64 v[196:197], v215 offset:17152
	ds_read_b64 v[204:205], v215 offset:34304
	ds_read_b64 v[230:231], v215 offset:51456
	v_exp_f32_e32 v60, v60
	v_exp_f32_e32 v179, v56
	v_exp_f32_e32 v56, v61
	v_exp_f32_e32 v61, v57
	v_exp_f32_e32 v57, v62
	v_exp_f32_e32 v62, v63
	v_exp_f32_e32 v63, v58
	v_exp_f32_e32 v59, v59
	v_cvt_pk_bf16_f32 v56, v60, v56
	v_cvt_pk_bf16_f32 v57, v57, v62
	v_cvt_pk_bf16_f32 v58, v179, v61
	v_cvt_pk_bf16_f32 v59, v63, v59
	s_waitcnt lgkmcnt(11)
	s_nop 0
	v_mfma_f32_16x16x32_bf16 v[36:39], v[44:47], v[56:59], v[36:39]
	s_waitcnt lgkmcnt(10)
	v_mfma_f32_16x16x32_bf16 v[44:47], v[216:219], v[56:59], v[52:55]
	s_waitcnt lgkmcnt(9)
	v_mfma_f32_16x16x32_bf16 v[52:55], v[220:223], v[56:59], v[180:183]
	s_waitcnt lgkmcnt(8)
	v_mfma_f32_16x16x32_bf16 v[60:63], v[224:227], v[56:59], v[184:187]
	s_mulk_i32 s85, 0x60
	v_add_u32_e32 v179, s85, v177
	v_mfma_f32_16x16x32_bf16 v[32:35], v[40:43], v[56:59], v[32:35]
	v_add_u32_e32 v215, s85, v178
	ds_read_b64 v[56:57], v179
	ds_read_b64 v[180:181], v179 offset:17152
	ds_read_b64 v[184:185], v179 offset:34304
	ds_read_b64 v[216:217], v179 offset:51456
	ds_read_b64 v[58:59], v215
	ds_read_b64 v[182:183], v215 offset:17152
	ds_read_b64 v[186:187], v215 offset:34304
	ds_read_b64 v[218:219], v215 offset:51456
	v_exp_f32_e32 v68, v68
	v_exp_f32_e32 v179, v64
	v_exp_f32_e32 v64, v69
	v_exp_f32_e32 v69, v65
	v_exp_f32_e32 v65, v70
	v_exp_f32_e32 v70, v71
	v_exp_f32_e32 v71, v66
	v_exp_f32_e32 v67, v67
	v_cvt_pk_bf16_f32 v64, v68, v64
	v_cvt_pk_bf16_f32 v65, v65, v70
	v_cvt_pk_bf16_f32 v66, v179, v69
	v_cvt_pk_bf16_f32 v67, v71, v67
	s_waitcnt lgkmcnt(11)
	s_nop 0
	v_mfma_f32_16x16x32_bf16 v[36:39], v[48:51], v[64:67], v[36:39]
	s_waitcnt lgkmcnt(10)
	v_mfma_f32_16x16x32_bf16 v[44:47], v[194:197], v[64:67], v[44:47]
	s_waitcnt lgkmcnt(9)
	v_mfma_f32_16x16x32_bf16 v[48:51], v[202:205], v[64:67], v[52:55]
	s_waitcnt lgkmcnt(8)
	v_mfma_f32_16x16x32_bf16 v[52:55], v[228:231], v[64:67], v[60:63]
	s_mulk_i32 s89, 0x60
	s_nop 1
	v_add_u32_e32 v62, s89, v177
	v_mfma_f32_16x16x32_bf16 v[32:35], v[40:43], v[64:67], v[32:35]
	v_add_u32_e32 v179, s89, v178
	ds_read_b64 v[60:61], v62
	ds_read_b64 v[64:65], v62 offset:17152
	ds_read_b64 v[68:69], v62 offset:34304
	ds_read_b64 v[194:195], v62 offset:51456
	ds_read_b64 v[62:63], v179
	ds_read_b64 v[66:67], v179 offset:17152
	ds_read_b64 v[70:71], v179 offset:34304
	ds_read_b64 v[196:197], v179 offset:51456
	v_exp_f32_e32 v76, v76
	v_exp_f32_e32 v179, v72
	v_exp_f32_e32 v72, v77
	v_exp_f32_e32 v77, v73
	v_exp_f32_e32 v73, v78
	v_exp_f32_e32 v78, v79
	v_exp_f32_e32 v79, v74
	v_exp_f32_e32 v75, v75
	v_cvt_pk_bf16_f32 v72, v76, v72
	v_cvt_pk_bf16_f32 v73, v73, v78
	v_cvt_pk_bf16_f32 v74, v179, v77
	v_cvt_pk_bf16_f32 v75, v79, v75
	s_waitcnt lgkmcnt(11)
	s_nop 0
	v_mfma_f32_16x16x32_bf16 v[36:39], v[56:59], v[72:75], v[36:39]
	s_waitcnt lgkmcnt(10)
	v_mfma_f32_16x16x32_bf16 v[44:47], v[180:183], v[72:75], v[44:47]
	s_waitcnt lgkmcnt(9)
	v_mfma_f32_16x16x32_bf16 v[48:51], v[184:187], v[72:75], v[48:51]
	s_waitcnt lgkmcnt(8)
	v_mfma_f32_16x16x32_bf16 v[52:55], v[216:219], v[72:75], v[52:55]
	s_mulk_i32 s94, 0x60
	v_add_u32_e32 v58, s94, v177
	v_mfma_f32_16x16x32_bf16 v[32:35], v[40:43], v[72:75], v[32:35]
	v_add_u32_e32 v179, s94, v178
	ds_read_b64 v[56:57], v58
	ds_read_b64 v[72:73], v58 offset:17152
	ds_read_b64 v[76:77], v58 offset:34304
	ds_read_b64 v[180:181], v58 offset:51456
	ds_read_b64 v[58:59], v179
	ds_read_b64 v[74:75], v179 offset:17152
	ds_read_b64 v[78:79], v179 offset:34304
	ds_read_b64 v[182:183], v179 offset:51456
	v_exp_f32_e32 v92, v92
	v_exp_f32_e32 v179, v88
	v_exp_f32_e32 v88, v93
	v_exp_f32_e32 v93, v89
	v_exp_f32_e32 v89, v94
	v_exp_f32_e32 v94, v95
	v_exp_f32_e32 v95, v90
	v_exp_f32_e32 v91, v91
	v_cvt_pk_bf16_f32 v88, v92, v88
	v_cvt_pk_bf16_f32 v89, v89, v94
	v_cvt_pk_bf16_f32 v90, v179, v93
	v_cvt_pk_bf16_f32 v91, v95, v91
	s_waitcnt lgkmcnt(11)
	s_nop 0
	v_mfma_f32_16x16x32_bf16 v[36:39], v[60:63], v[88:91], v[36:39]
	s_waitcnt lgkmcnt(10)
	v_mfma_f32_16x16x32_bf16 v[44:47], v[64:67], v[88:91], v[44:47]
	s_waitcnt lgkmcnt(9)
	v_mfma_f32_16x16x32_bf16 v[48:51], v[68:71], v[88:91], v[48:51]
	s_waitcnt lgkmcnt(8)
	v_mfma_f32_16x16x32_bf16 v[52:55], v[194:197], v[88:91], v[52:55]
	v_exp_f32_e32 v64, v96
	v_exp_f32_e32 v66, v80
	v_mfma_f32_16x16x32_bf16 v[60:63], v[40:43], v[88:91], v[32:35]
	v_exp_f32_e32 v67, v82
	v_exp_f32_e32 v68, v83
	s_nop 0
	v_exp_f32_e32 v32, v97
	v_exp_f32_e32 v33, v81
	v_exp_f32_e32 v34, v98
	v_exp_f32_e32 v35, v99
	v_cvt_pk_bf16_f32 v64, v64, v32
	v_cvt_pk_bf16_f32 v66, v66, v33
	v_cvt_pk_bf16_f32 v67, v67, v68
	v_cvt_pk_bf16_f32 v65, v34, v35
	s_waitcnt lgkmcnt(3)
	s_nop 0
	v_mfma_f32_16x16x32_bf16 v[36:39], v[56:59], v[64:67], v[36:39]
	s_waitcnt lgkmcnt(2)
	v_mfma_f32_16x16x32_bf16 v[56:59], v[72:75], v[64:67], v[44:47]
	s_waitcnt lgkmcnt(1)
	v_mfma_f32_16x16x32_bf16 v[44:47], v[76:79], v[64:67], v[48:51]
	s_waitcnt lgkmcnt(0)
	v_mfma_f32_16x16x32_bf16 v[32:35], v[180:183], v[64:67], v[52:55]
	v_mfma_f32_16x16x32_bf16 v[40:43], v[40:43], v[64:67], v[60:63]
	s_andn2_b64 vcc, exec, s[66:67]
	s_waitcnt vmcnt(3)
	s_nop 5
	v_lshlrev_b32_e32 v42, 16, v190
	v_mul_f32_e32 v41, 0xbfb8aa3b, v42
	v_exp_f32_e32 v41, v41
	v_rcp_f32_e32 v40, v40
	v_and_b32_e32 v43, 0xffff0000, v190
	v_add_f32_e32 v41, 1.0, v41
	v_rcp_f32_e32 v48, v41
	v_pk_mul_f32 v[36:37], v[36:37], v[40:41] op_sel_hi:[1,0]
	v_mul_f32_e32 v41, 0xbfb8aa3b, v43
	v_exp_f32_e32 v41, v41
	s_nop 0
	v_add_f32_e32 v41, 1.0, v41
	v_rcp_f32_e32 v49, v41
	v_pk_mul_f32 v[38:39], v[38:39], v[40:41] op_sel_hi:[1,0]
	v_pk_mul_f32 v[42:43], v[48:49], v[42:43]
	s_nop 0
	v_pk_mul_f32 v[36:37], v[42:43], v[36:37]
	v_lshlrev_b32_e32 v42, 16, v191
	v_cvt_pk_bf16_f32 v36, v36, v37
	v_mul_f32_e32 v37, 0xbfb8aa3b, v42
	v_exp_f32_e32 v37, v37
	v_and_b32_e32 v43, 0xffff0000, v191
	v_add_f32_e32 v37, 1.0, v37
	v_rcp_f32_e32 v48, v37
	v_mul_f32_e32 v37, 0xbfb8aa3b, v43
	v_exp_f32_e32 v37, v37
	s_nop 0
	v_add_f32_e32 v37, 1.0, v37
	v_rcp_f32_e32 v49, v37
	s_nop 0
	v_pk_mul_f32 v[42:43], v[48:49], v[42:43]
	s_nop 0
	v_pk_mul_f32 v[38:39], v[42:43], v[38:39]
	s_nop 0
	v_cvt_pk_bf16_f32 v37, v38, v39
	s_waitcnt vmcnt(2)
	v_lshlrev_b32_e32 v38, 16, v192
	v_mul_f32_e32 v41, 0xbfb8aa3b, v38
	v_exp_f32_e32 v41, v41
	v_and_b32_e32 v39, 0xffff0000, v192
	v_add_f32_e32 v41, 1.0, v41
	v_rcp_f32_e32 v42, v41
	v_pk_mul_f32 v[48:49], v[56:57], v[40:41] op_sel_hi:[1,0]
	v_mul_f32_e32 v41, 0xbfb8aa3b, v39
	v_exp_f32_e32 v41, v41
	s_nop 0
	v_add_f32_e32 v41, 1.0, v41
	v_rcp_f32_e32 v43, v41
	v_pk_mul_f32 v[50:51], v[58:59], v[40:41] op_sel_hi:[1,0]
	v_pk_mul_f32 v[38:39], v[42:43], v[38:39]
	s_nop 0
	v_pk_mul_f32 v[38:39], v[38:39], v[48:49]
	v_lshlrev_b32_e32 v42, 16, v193
	v_cvt_pk_bf16_f32 v38, v38, v39
	v_mul_f32_e32 v39, 0xbfb8aa3b, v42
	v_exp_f32_e32 v39, v39
	v_and_b32_e32 v43, 0xffff0000, v193
	v_permlane16_swap_b32_e32 v36, v38
	v_add_f32_e32 v39, 1.0, v39
	v_rcp_f32_e32 v48, v39
	v_mul_f32_e32 v39, 0xbfb8aa3b, v43
	v_exp_f32_e32 v39, v39
	s_nop 0
	v_add_f32_e32 v39, 1.0, v39
	v_rcp_f32_e32 v49, v39
	s_nop 0
	v_pk_mul_f32 v[42:43], v[48:49], v[42:43]
	s_nop 0
	v_pk_mul_f32 v[42:43], v[42:43], v[50:51]
	s_nop 0
	v_cvt_pk_bf16_f32 v39, v42, v43
	s_waitcnt vmcnt(1)
	v_lshlrev_b32_e32 v42, 16, v198
	v_mul_f32_e32 v41, 0xbfb8aa3b, v42
	v_exp_f32_e32 v41, v41
	v_and_b32_e32 v43, 0xffff0000, v198
	v_permlane16_swap_b32_e32 v37, v39
	v_add_f32_e32 v41, 1.0, v41
	v_rcp_f32_e32 v48, v41
	v_pk_mul_f32 v[44:45], v[44:45], v[40:41] op_sel_hi:[1,0]
	v_mul_f32_e32 v41, 0xbfb8aa3b, v43
	v_exp_f32_e32 v41, v41
	global_store_dwordx4 v[130:131], v[36:39], off
	v_add_f32_e32 v41, 1.0, v41
	v_rcp_f32_e32 v49, v41
	s_nop 0
	v_pk_mul_f32 v[42:43], v[48:49], v[42:43]
	s_nop 0
	v_pk_mul_f32 v[42:43], v[42:43], v[44:45]
	v_lshlrev_b32_e32 v44, 16, v199
	v_mul_f32_e32 v41, 0xbfb8aa3b, v44
	v_exp_f32_e32 v41, v41
	v_and_b32_e32 v45, 0xffff0000, v199
	v_cvt_pk_bf16_f32 v42, v42, v43
	v_add_f32_e32 v41, 1.0, v41
	v_rcp_f32_e32 v48, v41
	v_pk_mul_f32 v[46:47], v[46:47], v[40:41] op_sel_hi:[1,0]
	v_mul_f32_e32 v41, 0xbfb8aa3b, v45
	v_exp_f32_e32 v41, v41
	s_nop 0
	v_add_f32_e32 v41, 1.0, v41
	v_rcp_f32_e32 v49, v41
	s_nop 0
	v_pk_mul_f32 v[44:45], v[48:49], v[44:45]
	s_nop 0
	v_pk_mul_f32 v[44:45], v[44:45], v[46:47]
	s_nop 0
	v_cvt_pk_bf16_f32 v43, v44, v45
	s_waitcnt vmcnt(1)
	v_lshlrev_b32_e32 v44, 16, v200
	v_mul_f32_e32 v41, 0xbfb8aa3b, v44
	v_exp_f32_e32 v41, v41
	v_and_b32_e32 v45, 0xffff0000, v200
	v_add_f32_e32 v41, 1.0, v41
	v_rcp_f32_e32 v46, v41
	v_pk_mul_f32 v[32:33], v[32:33], v[40:41] op_sel_hi:[1,0]
	v_mul_f32_e32 v41, 0xbfb8aa3b, v45
	v_exp_f32_e32 v41, v41
	s_nop 0
	v_add_f32_e32 v41, 1.0, v41
	v_rcp_f32_e32 v47, v41
	s_nop 0
	v_pk_mul_f32 v[44:45], v[46:47], v[44:45]
	s_nop 0
	v_pk_mul_f32 v[32:33], v[44:45], v[32:33]
	s_nop 0
	v_cvt_pk_bf16_f32 v44, v32, v33
	v_lshlrev_b32_e32 v32, 16, v201
	v_mul_f32_e32 v41, 0xbfb8aa3b, v32
	v_exp_f32_e32 v41, v41
	v_and_b32_e32 v33, 0xffff0000, v201
	v_mov_b64_e32 v[190:191], 0x200
	v_mov_b64_e32 v[192:193], 0x1ff
	v_mov_b64_e32 v[198:199], 0x600
	v_mov_b64_e32 v[200:201], 0x5ff
	v_mov_b64_e32 v[210:211], 0x4ff
	v_permlane16_swap_b32_e32 v42, v44
	v_add_f32_e32 v41, 1.0, v41
	v_pk_mul_f32 v[34:35], v[34:35], v[40:41] op_sel_hi:[1,0]
	v_mul_f32_e32 v40, 0xbfb8aa3b, v33
	v_exp_f32_e32 v40, v40
	v_rcp_f32_e32 v46, v41
	v_add_f32_e32 v40, 1.0, v40
	v_rcp_f32_e32 v47, v40
	s_nop 0
	v_pk_mul_f32 v[32:33], v[46:47], v[32:33]
	s_nop 0
	v_pk_mul_f32 v[32:33], v[32:33], v[34:35]
	s_nop 0
	v_cvt_pk_bf16_f32 v45, v32, v33
	s_nop 1
	v_permlane16_swap_b32_e32 v43, v45
	global_store_dwordx4 v[128:129], v[42:45], off
	s_waitcnt lgkmcnt(0)
	s_barrier
	s_cbranch_vccnz .LBB0_489
	v_cmp_gt_i32_e32 vcc, s88, v145
	s_and_saveexec_b64 s[66:67], vcc
	s_cbranch_execnz .LBB0_495
	s_or_b64 exec, exec, s[66:67]
	v_cmp_gt_i32_e32 vcc, s88, v146
	s_and_saveexec_b64 s[66:67], vcc
	s_cbranch_execnz .LBB0_496
